# rotation relocation in all five conversion loops, every no-next path routed through the rotation
# speedup vs baseline: 1.0105x; 1.0046x over previous
.LBB0_13:
	s_and_b64 vcc, exec, s[0:1]
	s_cbranch_vccz .LBB0_504
	v_readlane_b32 s0, v251, 52
	v_readlane_b32 s1, v251, 53
	s_andn2_b64 vcc, exec, s[0:1]
	s_cbranch_vccnz .LBB0_47
	v_ashrrev_i32_e32 v21, 4, v142
	v_readlane_b32 s0, v252, 8
	v_ashrrev_i32_e32 v25, 3, v142
	s_waitcnt vmcnt(0)
	v_lshl_add_u32 v5, v25, 2, 0
	v_add_u32_e32 v0, s0, v21
	v_readlane_b32 s0, v252, 9
	v_readlane_b32 s1, v252, 10
	v_readlane_b32 s33, v250, 0
	v_readlane_b32 s30, v251, 54
	v_mov_b64_e32 v[2:3], s[0:1]
	s_movk_i32 s0, 0x2c00
	v_mad_i64_i32 v[2:3], s[0:1], v0, s0, v[2:3]
	v_lshlrev_b32_e32 v0, 2, v142
	v_and_b32_e32 v4, 60, v0
	v_lshlrev_b32_e32 v0, 2, v4
	v_lshl_add_u64 v[2:3], v[2:3], 0, v[0:1]
	v_add_co_u32_e32 v6, vcc, 0x58000, v2
	s_movk_i32 s0, 0x104
	s_nop 0
	v_addc_co_u32_e32 v7, vcc, 0, v3, vcc
	global_load_dwordx4 v[12:15], v[2:3], off nt
	global_load_dwordx4 v[16:19], v[6:7], off nt
	v_mul_lo_u32 v2, v21, s0
	v_add3_u32 v24, 0, v2, v0
	v_lshlrev_b32_e32 v0, 3, v142
	v_and_b32_e32 v20, 56, v0
	v_mul_u32_u24_e32 v6, 0x104, v20
	v_mov_b32_e32 v2, v1
	v_mov_b32_e32 v3, v1
	v_mov_b32_e32 v0, v1
	v_lshlrev_b32_e32 v22, 2, v4
	v_add_u32_e32 v26, v5, v6
	v_mov_b64_e32 v[6:7], v[2:3]
	v_mov_b64_e32 v[10:11], v[2:3]
	v_mov_b64_e32 v[4:5], v[0:1]
	v_mov_b64_e32 v[8:9], v[0:1]
	v_readlane_b32 s22, v252, 7
	s_waitcnt vmcnt(0)
	v_mov_b64_e32 v[10:11], v[18:19]
	v_mov_b64_e32 v[6:7], v[14:15]
	v_mov_b64_e32 v[4:5], v[12:13]
	v_mov_b64_e32 v[8:9], v[16:17]
	s_branch .LBB0_20
.Lcvr_LBB0_20:
	s_waitcnt vmcnt(1)
	v_mov_b64_e32 v[18:19], v[10:11]
	v_mov_b64_e32 v[14:15], v[6:7]
	v_mov_b64_e32 v[12:13], v[4:5]
	v_mov_b64_e32 v[16:17], v[8:9]
	s_branch .LBB0_25
.LBB0_16:
	s_or_b64 exec, exec, s[30:31]

.LBB0_19:
	v_ashrrev_i32_e32 v3, 31, v2
	v_readlane_b32 s22, v253, 31
	v_lshlrev_b64 v[2:3], 11, v[2:3]
	v_readlane_b32 s23, v253, 32
	s_ashr_i32 s21, s20, 31
	v_lshlrev_b32_e32 v0, 1, v20
	v_lshl_add_u64 v[2:3], s[22:23], 0, v[2:3]
	v_lshl_add_u64 v[2:3], s[20:21], 1, v[2:3]
	v_lshl_add_u64 v[2:3], v[2:3], 0, v[0:1]
	global_store_dwordx4 v[2:3], v[12:15], off
	s_andn2_b64 vcc, exec, s[2:3]
	s_mov_b32 s30, s35
	s_mov_b32 s22, s36
	s_barrier
	s_cbranch_vccz .LBB0_47

.LBB0_24:
	s_mul_hi_i32 s20, s36, 0x2e8ba2e9
	s_lshr_b32 s21, s20, 31
	s_ashr_i32 s20, s20, 3
	s_add_i32 s20, s20, s21
	s_mul_i32 s21, s20, 0xffffffd4
	v_lshl_add_u32 v0, s20, 6, v21
	v_mov_b64_e32 v[2:3], s[0:1]
	s_movk_i32 s20, 0x2c00
	s_add_i32 s23, s21, s36
	v_mad_i64_i32 v[2:3], s[20:21], v0, s20, v[2:3]
	s_lshl_b32 s20, s23, 6
	s_ashr_i32 s21, s20, 31
	v_lshl_add_u64 v[2:3], s[20:21], 2, v[2:3]
	v_mov_b32_e32 v23, v1
	v_lshl_add_u64 v[2:3], v[2:3], 0, v[22:23]
	s_waitcnt vmcnt(1)
	v_mov_b64_e32 v[18:19], v[10:11]
	v_mov_b64_e32 v[14:15], v[6:7]
	v_mov_b64_e32 v[12:13], v[4:5]
	v_mov_b64_e32 v[16:17], v[8:9]
	v_add_co_u32_e32 v8, vcc, 0x58000, v2
	s_nop 1
	v_addc_co_u32_e32 v9, vcc, 0, v3, vcc
	global_load_dwordx4 v[4:7], v[2:3], off nt
	s_nop 0
	global_load_dwordx4 v[8:11], v[8:9], off nt
